# per-XCC workgroup-count discovery moved from the first full grid barrier into the light P0->P1 wait (off the barrier's critical path)
# baseline (speedup 1.0000x reference)
.Lgb1_spin:
	global_load_dword v1, v0, s[54:55] sc1
	s_waitcnt vmcnt(0)
	v_readfirstlane_b32 s0, v1
	s_cmp_ge_u32 s0, s34
	s_cbranch_scc1 .Lgb1_disc
	s_sleep 1
	s_add_u32 s1, s1, 1
	s_cmp_lt_u32 s1, 0x40000
	s_cbranch_scc1 .Lgb1_spin
	s_branch .LBB0_92
.Lgb1_disc:
	s_getreg_b32 s0, hwreg(HW_REG_XCC_ID, 0, 4)
	s_and_b32 s0, s0, 15
	v_readlane_b32 s1, v255, 0
	s_mul_i32 s1, s35, s1
	s_mul_i32 s15, s1, s34
	s_mov_b32 s1, 0
	v_mov_b32_e32 v0, 0x400

.Lgb1_cntok:
	s_max_u32 s8, s14, 1
	s_max_u32 s9, s9, 1
	v_mov_b32_e32 v0, 0x23fc0
	v_mov_b32_e32 v2, s8
	v_mov_b32_e32 v3, s9
	ds_write_b64 v0, v[2:3]
	s_branch .LBB0_92

.LBB0_132:
	s_add_u32 s12, s54, 0x200
	s_addc_u32 s13, s55, 0
	s_add_u32 s18, s54, 0x1000
	s_addc_u32 s19, s55, 0
	s_add_u32 s20, s54, 0x1100
	s_addc_u32 s21, s55, 0
	s_add_u32 s22, s54, 0x1200
	s_addc_u32 s23, s55, 0
	s_add_u32 s24, s54, 0x1300
	s_mul_i32 s83, s35, s34
	v_readlane_b32 s0, v255, 0
	s_addc_u32 s25, s55, 0
	s_mul_i32 s83, s83, s0
	s_add_u32 s0, s54, 0x3400
	s_addc_u32 s1, s55, 0
	v_writelane_b32 v255, s0, 6
	s_barrier
	s_nop 0
	v_writelane_b32 v255, s1, 7
	s_add_u32 s0, s54, 0x3500
	s_addc_u32 s1, s55, 0
	s_waitcnt vmcnt(0)
	v_writelane_b32 v255, s0, 8
	s_barrier
	s_nop 0
	v_writelane_b32 v255, s1, 9
	s_mov_b64 s[4:5], exec
	v_readlane_b32 s0, v255, 1
	v_readlane_b32 s1, v255, 2
	s_and_b64 s[0:1], s[4:5], s[0:1]
	s_mov_b64 exec, s[0:1]
	s_cbranch_execz .Lgb2_others
	s_getreg_b32 s0, hwreg(HW_REG_XCC_ID, 0, 4)
	v_mov_b32_e32 v0, 0x23fc0
	ds_read_b64 v[2:3], v0
	s_and_b32 s0, s0, 15
	s_lshl_b32 s1, s0, 8
	s_add_u32 s6, s54, s1
	s_addc_u32 s7, s55, 0
	v_mov_b32_e32 v0, 0x1000
	v_mov_b32_e32 v1, 1
	global_atomic_add v1, v0, v1, s[6:7] offset:1024 sc0
	s_waitcnt lgkmcnt(0)
	v_readfirstlane_b32 s8, v2
	v_readfirstlane_b32 s9, v3
	s_mul_i32 s8, s8, 1
	s_mul_i32 s9, s9, 1
	v_mov_b32_e32 v0, 0x3000
	s_waitcnt vmcnt(0)
	v_readfirstlane_b32 s0, v1
	s_add_u32 s0, s0, 1
	s_cmp_lg_u32 s0, s8
	s_cbranch_scc0 .Lgb2_lead
	s_branch .Lgb2_wait
